# PRO: weight-tile and x-row loads marked nt (read once); stacked on the ERES nt loads
# speedup vs baseline: 1.0229x; 1.0031x over previous
.LBB0_619:
	v_ashrrev_i32_e32 v10, 4, v208
	v_and_b32_e32 v0, 60, v34
	v_ashrrev_i32_e32 v11, 31, v10
	v_lshlrev_b32_e32 v0, 2, v0
	v_mul_lo_u32 v4, s38, v11
	v_mul_lo_u32 v5, s39, v10
	s_waitcnt lgkmcnt(0)
	v_mad_u64_u32 v[2:3], s[18:19], s38, v10, 0
	v_lshl_add_u64 v[6:7], s[36:37], 0, v[0:1]
	v_add3_u32 v3, v3, v4, v5
	v_lshl_add_u64 v[2:3], v[2:3], 2, v[6:7]
	global_load_dwordx4 v[2:5], v[2:3], off nt
	s_cmp_lg_u64 s[40:41], 0
	s_cselect_b64 s[30:31], -1, 0
	s_cmp_eq_u64 s[40:41], 0
	v_lshl_add_u64 v[14:15], v[10:11], 2, s[40:41]
	s_cbranch_scc1 .LBB0_621
	global_load_dword v8, v[14:15], off
	s_waitcnt vmcnt(0)
	v_pk_mul_f32 v[4:5], v[4:5], v[8:9] op_sel_hi:[1,0]
	v_pk_mul_f32 v[2:3], v[2:3], v[8:9] op_sel_hi:[1,0]
.LBB0_621:
	v_add_u32_e32 v12, 32, v10
	v_ashrrev_i32_e32 v13, 31, v12
	v_mul_lo_u32 v16, s38, v13
	v_mul_lo_u32 v17, s39, v12
	v_mad_u64_u32 v[8:9], s[18:19], s38, v12, 0
	v_add3_u32 v9, v9, v16, v17
	v_lshl_add_u64 v[6:7], v[8:9], 2, v[6:7]
	global_load_dwordx4 v[6:9], v[6:7], off nt
	s_andn2_b64 vcc, exec, s[30:31]
	s_cbranch_vccnz .LBB0_623
	global_load_dword v14, v[14:15], off offset:128
	s_waitcnt vmcnt(0)
	v_pk_mul_f32 v[8:9], v[8:9], v[14:15] op_sel_hi:[1,0]
	v_pk_mul_f32 v[6:7], v[6:7], v[14:15] op_sel_hi:[1,0]

.LBB0_641:
	v_lshl_add_u64 v[6:7], s[36:37], 0, v[0:1]
	v_mul_lo_u32 v4, s41, v10
	v_mul_lo_u32 v5, s40, v11
	v_mad_u64_u32 v[2:3], s[36:37], s40, v10, 0
	v_add3_u32 v3, v3, v5, v4
	v_lshl_add_u64 v[2:3], v[2:3], 2, v[6:7]
	global_load_dwordx4 v[2:5], v[2:3], off nt
	s_cmp_lg_u64 s[38:39], 0
	s_cselect_b64 s[36:37], -1, 0
	s_mov_b64 s[50:51], s[36:37]
	s_cmp_eq_u64 s[38:39], 0
	v_lshl_add_u64 v[18:19], v[10:11], 2, s[38:39]
	s_cbranch_scc1 .LBB0_643
	global_load_dword v32, v[18:19], off
.LBB0_643:
	v_mul_lo_u32 v17, s41, v12
	v_mul_lo_u32 v23, s40, v13
	v_mad_u64_u32 v[8:9], s[38:39], s40, v12, 0
	v_add3_u32 v9, v9, v23, v17
	v_lshl_add_u64 v[6:7], v[8:9], 2, v[6:7]
	global_load_dwordx4 v[6:9], v[6:7], off nt
	s_andn2_b64 vcc, exec, s[36:37]
	s_cbranch_vccnz .LBB0_624
	global_load_dword v36, v[18:19], off offset:128
	s_branch .LBB0_624

.LBB0_649:
	s_mov_b32 s6, 0x8000
	v_add_u32_e32 v0, 0xffff8000, v38
	v_cmp_gt_i32_e32 vcc, s6, v38
	v_ashrrev_i32_e32 v39, 31, v38
	v_mov_b32_e32 v4, s53
	s_waitcnt lgkmcnt(0)
	v_cndmask_b32_e32 v2, v0, v38, vcc
	v_mov_b32_e32 v0, s55
	s_waitcnt lgkmcnt(0)
	v_cndmask_b32_e32 v3, 0, v39, vcc
	v_cndmask_b32_e32 v5, v0, v4, vcc
	v_mov_b32_e32 v0, s54
	v_mov_b32_e32 v4, s52
	v_cndmask_b32_e32 v4, v0, v4, vcc
	v_lshlrev_b64 v[2:3], 12, v[2:3]
	v_lshl_add_u64 v[2:3], v[4:5], 0, v[2:3]
	v_lshlrev_b32_e32 v0, 2, v34
	v_cmp_ne_u64_e32 vcc, 0, v[4:5]
	v_lshl_add_u64 v[2:3], v[2:3], 0, v[0:1]
	v_mov_b32_e32 v14, 0
	v_mov_b32_e32 v26, 0
	v_mov_b32_e32 v27, 0
	v_mov_b32_e32 v28, 0
	v_mov_b32_e32 v29, 0
	s_and_saveexec_b64 s[40:41], vcc
	s_cbranch_execz .LBB0_651
	global_load_dwordx4 v[26:29], v[2:3], off nt
.LBB0_651:
	s_or_b64 exec, exec, s[40:41]
	v_mov_b32_e32 v15, 0
	v_mov_b32_e32 v16, 0
	v_mov_b32_e32 v17, 0
	s_and_saveexec_b64 s[40:41], vcc
	s_cbranch_execz .LBB0_653
	global_load_dwordx4 v[14:17], v[2:3], off offset:1024 nt
.LBB0_653:
	s_or_b64 exec, exec, s[40:41]
	v_mov_b32_e32 v22, 0
	v_mov_b32_e32 v30, 0
	v_mov_b32_e32 v31, 0
	v_mov_b32_e32 v32, 0
	v_mov_b32_e32 v33, 0
	s_and_saveexec_b64 s[40:41], vcc
	s_cbranch_execz .LBB0_655
	global_load_dwordx4 v[30:33], v[2:3], off offset:2048 nt
.LBB0_655:
	s_or_b64 exec, exec, s[40:41]
	v_mov_b32_e32 v23, 0
	v_mov_b32_e32 v24, 0
	v_mov_b32_e32 v25, 0
	s_and_saveexec_b64 s[40:41], vcc
	s_cbranch_execz .LBB0_657
	global_load_dwordx4 v[22:25], v[2:3], off offset:3072 nt
.LBB0_657:
	s_or_b64 exec, exec, s[40:41]
	v_add_u32_e32 v40, s2, v38
	v_cmp_lt_i32_e32 vcc, s4, v40
	s_and_saveexec_b64 s[14:15], vcc
	s_xor_b64 s[40:41], exec, s[14:15]
	v_add_u32_e32 v2, 0xffff8000, v40
	v_mov_b32_e32 v3, v1
	v_lshlrev_b64 v[2:3], 12, v[2:3]
	v_lshl_add_u64 v[2:3], s[54:55], 0, v[2:3]
	v_cmp_gt_u32_e32 vcc, s49, v40
	s_nop 1
	v_cndmask_b32_e32 v3, 0, v3, vcc
	v_cndmask_b32_e32 v2, 0, v2, vcc
	s_or_saveexec_b64 s[40:41], s[40:41]
	v_ashrrev_i32_e32 v41, 31, v40
	s_xor_b64 exec, exec, s[40:41]
	v_lshlrev_b64 v[2:3], 12, v[40:41]
	v_lshl_add_u64 v[2:3], s[52:53], 0, v[2:3]
	s_or_b64 exec, exec, s[40:41]
	v_cmp_ne_u64_e32 vcc, 0, v[2:3]
	v_cmp_gt_i32_e64 s[40:41], s49, v40
	s_and_b64 s[42:43], s[40:41], vcc
	v_lshl_add_u64 v[42:43], v[2:3], 0, v[0:1]
	v_mov_b32_e32 v2, 0
	v_mov_b32_e32 v10, 0
	v_mov_b32_e32 v11, 0
	v_mov_b32_e32 v12, 0
	v_mov_b32_e32 v13, 0
	s_and_saveexec_b64 s[44:45], s[42:43]
	s_cbranch_execz .LBB0_663
	global_load_dwordx4 v[10:13], v[42:43], off nt
.LBB0_663:
	s_or_b64 exec, exec, s[44:45]
	v_mov_b32_e32 v3, 0
	v_mov_b32_e32 v4, 0
	v_mov_b32_e32 v5, 0
	s_and_saveexec_b64 s[44:45], s[42:43]
	s_cbranch_execz .LBB0_665
	global_load_dwordx4 v[2:5], v[42:43], off offset:1024 nt
.LBB0_665:
	s_or_b64 exec, exec, s[44:45]
	v_mov_b32_e32 v6, 0
	v_mov_b32_e32 v18, 0
	v_mov_b32_e32 v19, 0
	v_mov_b32_e32 v20, 0
	v_mov_b32_e32 v21, 0
	s_and_saveexec_b64 s[44:45], s[42:43]
	s_cbranch_execz .LBB0_667
	global_load_dwordx4 v[18:21], v[42:43], off offset:2048 nt
.LBB0_667:
	s_or_b64 exec, exec, s[44:45]
	v_mov_b32_e32 v7, 0
	v_mov_b32_e32 v8, 0
	v_mov_b32_e32 v9, 0
	s_and_saveexec_b64 s[44:45], s[42:43]
	s_cbranch_execz .LBB0_669
	global_load_dwordx4 v[6:9], v[42:43], off offset:3072 nt
